# scan: gate-weight staging and the first unit's loads in one round trip (were 7 serialized); on top of FFN-in epilogue v2
# speedup vs baseline: 1.0171x; 1.0006x over previous
.Lscan1_unit:
	s_and_b32 s37, s23, 15
	s_lshr_b32 s0, s23, 4
	s_lshl_b32 s0, s0, 3
	s_add_i32 s0, s0, s21
	s_mul_i32 s55, s0, 0x5f5
	s_lshr_b32 s55, s55, 16
	s_mul_i32 s56, s55, 43
	s_sub_i32 s56, s0, s56
	s_mul_i32 s57, s55, 0x810
	s_mul_i32 s39, s56, 48
	s_add_i32 s57, s57, s39
	s_mul_i32 s44, s57, 0x1800
	s_mul_hi_u32 s45, s57, 0x1800
	s_mul_i32 s39, s37, 0xc0
	s_add_i32 s39, s39, 0xc00
	s_add_u32 s44, s44, s39
	s_addc_u32 s45, s45, 0
	s_add_u32 s44, s44, s28
	s_addc_u32 s45, s45, s29
	s_add_u32 s62, s44, 0xffffb800
	s_addc_u32 s63, s45, -1
	global_load_dword v59, v233, s[62:63]
	s_add_u32 s62, s62, 0x1800
	s_addc_u32 s63, s63, 0
	global_load_dword v61, v233, s[62:63]
	s_add_u32 s62, s62, 0x1800
	s_addc_u32 s63, s63, 0
	global_load_dword v63, v233, s[62:63]
	s_mov_b64 s[62:63], s[44:45]
	global_load_dword v66, v233, s[62:63]
	s_add_u32 s62, s62, 0x1800
	s_addc_u32 s63, s63, 0
	global_load_dword v67, v233, s[62:63]
	s_add_u32 s62, s62, 0x1800
	s_addc_u32 s63, s63, 0
	global_load_dword v68, v233, s[62:63]
	s_add_u32 s62, s62, 0x1800
	s_addc_u32 s63, s63, 0
	global_load_dword v69, v233, s[62:63]
	s_add_u32 s62, s62, 0x1800
	s_addc_u32 s63, s63, 0
	global_load_dword v70, v233, s[62:63]
	s_add_u32 s62, s62, 0x1800
	s_addc_u32 s63, s63, 0
	global_load_dword v71, v233, s[62:63]
	s_add_u32 s62, s62, 0x1800
	s_addc_u32 s63, s63, 0
	global_load_dword v72, v233, s[62:63]
	s_add_u32 s62, s62, 0x1800
	s_addc_u32 s63, s63, 0
	global_load_dword v73, v233, s[62:63]
	s_add_u32 s62, s62, 0x1800
	s_addc_u32 s63, s63, 0
	global_load_dword v74, v233, s[62:63]
	s_add_u32 s62, s62, 0x1800
	s_addc_u32 s63, s63, 0
	global_load_dword v75, v233, s[62:63]
	s_add_u32 s62, s62, 0x1800
	s_addc_u32 s63, s63, 0
	global_load_dword v76, v233, s[62:63]
	s_add_u32 s62, s62, 0x1800
	s_addc_u32 s63, s63, 0
	global_load_dword v77, v233, s[62:63]
	s_add_u32 s62, s62, 0x1800
	s_addc_u32 s63, s63, 0
	global_load_dword v78, v233, s[62:63]
	s_add_u32 s62, s62, 0x1800
	s_addc_u32 s63, s63, 0
	global_load_dword v79, v233, s[62:63]
	s_add_u32 s62, s62, 0x1800
	s_addc_u32 s63, s63, 0
	global_load_dword v80, v233, s[62:63]
	s_add_u32 s62, s62, 0x1800
	s_addc_u32 s63, s63, 0
	global_load_dword v81, v233, s[62:63]
	s_add_u32 s62, s62, 0x1800
	s_addc_u32 s63, s63, 0
	s_mov_b64 s[44:45], s[62:63]
	s_mul_i32 s39, s37, 0x180
	s_add_u32 s62, s8, s39
	s_addc_u32 s63, s9, 0
	global_load_dwordx2 v[48:49], v234, s[62:63]
	s_add_u32 s62, s62, 0x1800
	s_addc_u32 s63, s63, 0
	global_load_dwordx2 v[50:51], v234, s[62:63]
	s_add_u32 s62, s62, 0x1800
	s_addc_u32 s63, s63, 0
	global_load_dwordx2 v[52:53], v234, s[62:63]
	s_add_u32 s62, s62, 0x1800
	s_addc_u32 s63, s63, 0
	global_load_dwordx2 v[54:55], v234, s[62:63]
	s_add_u32 s62, s10, s39
	s_addc_u32 s63, s11, 0
	global_load_dwordx2 v[56:57], v234, s[62:63]
	s_mul_i32 s39, s55, 43
	s_add_i32 s39, s39, s56
	s_mul_i32 s39, s39, 0x1800
	s_mul_i32 s0, s37, 0x180
	s_add_i32 s39, s39, s0
	s_add_u32 s62, s30, s39
	s_addc_u32 s63, s31, 0
	v_mov_b32_e32 v0, 0
	v_mov_b32_e32 v24, 1.0
	v_mov_b32_e32 v1, 0
	v_mov_b32_e32 v25, 1.0
	v_mov_b32_e32 v2, 0
	v_mov_b32_e32 v26, 1.0
	v_mov_b32_e32 v3, 0
	v_mov_b32_e32 v27, 1.0
	v_mov_b32_e32 v4, 0
	v_mov_b32_e32 v28, 1.0
	v_mov_b32_e32 v5, 0
	v_mov_b32_e32 v29, 1.0
	v_mov_b32_e32 v6, 0
	v_mov_b32_e32 v30, 1.0
	v_mov_b32_e32 v7, 0
	v_mov_b32_e32 v31, 1.0
	v_mov_b32_e32 v8, 0
	v_mov_b32_e32 v32, 1.0
	v_mov_b32_e32 v9, 0
	v_mov_b32_e32 v33, 1.0
	v_mov_b32_e32 v10, 0
	v_mov_b32_e32 v34, 1.0
	v_mov_b32_e32 v11, 0
	v_mov_b32_e32 v35, 1.0
	v_mov_b32_e32 v12, 0
	v_mov_b32_e32 v36, 1.0
	v_mov_b32_e32 v13, 0
	v_mov_b32_e32 v37, 1.0
	v_mov_b32_e32 v14, 0
	v_mov_b32_e32 v38, 1.0
	v_mov_b32_e32 v15, 0
	v_mov_b32_e32 v39, 1.0
	v_mov_b32_e32 v16, 0
	v_mov_b32_e32 v40, 1.0
	v_mov_b32_e32 v17, 0
	v_mov_b32_e32 v41, 1.0
	v_mov_b32_e32 v18, 0
	v_mov_b32_e32 v42, 1.0
	v_mov_b32_e32 v19, 0
	v_mov_b32_e32 v43, 1.0
	v_mov_b32_e32 v20, 0
	v_mov_b32_e32 v44, 1.0
	v_mov_b32_e32 v21, 0
	v_mov_b32_e32 v45, 1.0
	v_mov_b32_e32 v22, 0
	v_mov_b32_e32 v46, 1.0
	v_mov_b32_e32 v23, 0
	v_mov_b32_e32 v47, 1.0
	s_mov_b64 s[6:7], s[62:63]
	s_cmp_eq_u32 s37, s38
	s_cbranch_scc1 .Lscan1_staged
	s_lshl_b32 s0, s20, 4
	s_add_i32 s0, s0, s37
	s_mul_i32 s0, s0, 0x4800
	s_add_u32 s62, s16, 0x3688000
	s_addc_u32 s63, s17, 0
	s_add_u32 s62, s62, s0
	s_addc_u32 s63, s63, 0
	v_add_u32_e32 v239, 0, v192
	v_mul_u32_u24_e32 v240, 0xaaab, v239
	v_lshrrev_b32_e32 v240, 19, v240
	v_mul_u32_u24_e32 v241, 12, v240
	v_sub_u32_e32 v241, v239, v241
	v_lshlrev_b32_e32 v241, 4, v241
	v_mul_u32_u24_e32 v118, 0xd0, v240
	v_add_u32_e32 v118, v118, v241
	v_mul_u32_u24_e32 v243, 0xc0, v240
	v_add_u32_e32 v243, v243, v241
	v_cmp_lt_u32_e32 vcc, 95, v240
	s_nop 1
	v_mov_b32_e32 v244, 0x8b800
	v_cndmask_b32_e32 v244, 0, v244, vcc
	v_add_u32_e32 v243, v243, v244
	global_load_dwordx4 v[98:101], v243, s[62:63]
	v_add_u32_e32 v239, 512, v192
	v_mul_u32_u24_e32 v240, 0xaaab, v239
	v_lshrrev_b32_e32 v240, 19, v240
	v_mul_u32_u24_e32 v241, 12, v240
	v_sub_u32_e32 v241, v239, v241
	v_lshlrev_b32_e32 v241, 4, v241
	v_mul_u32_u24_e32 v119, 0xd0, v240
	v_add_u32_e32 v119, v119, v241
	v_mul_u32_u24_e32 v243, 0xc0, v240
	v_add_u32_e32 v243, v243, v241
	v_cmp_lt_u32_e32 vcc, 95, v240
	s_nop 1
	v_mov_b32_e32 v244, 0x8b800
	v_cndmask_b32_e32 v244, 0, v244, vcc
	v_add_u32_e32 v243, v243, v244
	global_load_dwordx4 v[102:105], v243, s[62:63]
	v_add_u32_e32 v239, 1024, v192
	v_mul_u32_u24_e32 v240, 0xaaab, v239
	v_lshrrev_b32_e32 v240, 19, v240
	v_mul_u32_u24_e32 v241, 12, v240
	v_sub_u32_e32 v241, v239, v241
	v_lshlrev_b32_e32 v241, 4, v241
	v_mul_u32_u24_e32 v120, 0xd0, v240
	v_add_u32_e32 v120, v120, v241
	v_mul_u32_u24_e32 v243, 0xc0, v240
	v_add_u32_e32 v243, v243, v241
	v_cmp_lt_u32_e32 vcc, 95, v240
	s_nop 1
	v_mov_b32_e32 v244, 0x8b800
	v_cndmask_b32_e32 v244, 0, v244, vcc
	v_add_u32_e32 v243, v243, v244
	global_load_dwordx4 v[106:109], v243, s[62:63]
	v_add_u32_e32 v239, 1536, v192
	v_mul_u32_u24_e32 v240, 0xaaab, v239
	v_lshrrev_b32_e32 v240, 19, v240
	v_mul_u32_u24_e32 v241, 12, v240
	v_sub_u32_e32 v241, v239, v241
	v_lshlrev_b32_e32 v241, 4, v241
	v_mul_u32_u24_e32 v121, 0xd0, v240
	v_add_u32_e32 v121, v121, v241
	v_mul_u32_u24_e32 v243, 0xc0, v240
	v_add_u32_e32 v243, v243, v241
	v_cmp_lt_u32_e32 vcc, 95, v240
	s_nop 1
	v_mov_b32_e32 v244, 0x8b800
	v_cndmask_b32_e32 v244, 0, v244, vcc
	v_add_u32_e32 v243, v243, v244
	global_load_dwordx4 v[110:113], v243, s[62:63]
	v_add_u32_e32 v239, 2048, v192
	v_mul_u32_u24_e32 v240, 0xaaab, v239
	v_lshrrev_b32_e32 v240, 19, v240
	v_mul_u32_u24_e32 v241, 12, v240
	v_sub_u32_e32 v241, v239, v241
	v_lshlrev_b32_e32 v241, 4, v241
	v_mul_u32_u24_e32 v122, 0xd0, v240
	v_add_u32_e32 v122, v122, v241
	v_mul_u32_u24_e32 v243, 0xc0, v240
	v_add_u32_e32 v243, v243, v241
	v_cmp_lt_u32_e32 vcc, 95, v240
	s_nop 1
	v_mov_b32_e32 v244, 0x8b800
	v_cndmask_b32_e32 v244, 0, v244, vcc
	v_add_u32_e32 v243, v243, v244
	v_cmp_gt_u32_e32 vcc, 0x900, v239
	s_and_b64 exec, exec, vcc
	global_load_dwordx4 v[114:117], v243, s[62:63]
	s_mov_b64 exec, -1
	v_cmp_gt_u32_e32 vcc, 0x60, v192
	s_and_b64 exec, exec, vcc
	s_mul_i32 s0, s37, 0x180
	v_lshl_add_u32 v239, v192, 2, s0
	global_load_dword v123, v239, s[12:13]
	global_load_dword v124, v239, s[24:25]
	global_load_dword v125, v239, s[26:27]
	s_mov_b64 exec, -1
	s_waitcnt lgkmcnt(0)
	s_barrier
	s_waitcnt vmcnt(0)
	ds_write_b128 v118, v[98:101]
	ds_write_b128 v119, v[102:105]
	ds_write_b128 v120, v[106:109]
	ds_write_b128 v121, v[110:113]
	v_cmp_gt_u32_e32 vcc, 0x100, v192
	s_and_b64 exec, exec, vcc
	ds_write_b128 v122, v[114:117]
	s_mov_b64 exec, -1
	v_cmp_gt_u32_e32 vcc, 0x60, v192
	s_and_b64 exec, exec, vcc
	v_lshlrev_b32_e32 v240, 2, v192
	v_mul_f32_e32 v123, 0xbfb8aa3b, v123
	v_mul_f32_e32 v124, 0xbfb8aa3b, v124
	ds_write_b32 v240, v123 offset:39936
	ds_write_b32 v240, v124 offset:40320
	v_mul_f32_e32 v244, 0xbfb8aa3b, v125
	v_exp_f32_e32 v244, v244
	s_nop 0
	v_add_f32_e32 v245, 1.0, v244
	v_log_f32_e32 v245, v245
	v_fmamk_f32 v246, v244, 0xbe800000, v194
	v_fma_f32 v246, -v244, v246, 0.5
	v_fma_f32 v246, -v244, v246, 1.0
	v_mul_f32_e32 v246, v244, v246
	v_mul_f32_e32 v247, 0x3f317217, v245
	v_fma_f32 v247, v245, s76, -v247
	v_fmac_f32_e32 v247, 0x3377d1cf, v245
	v_fmac_f32_e32 v247, 0x3f317217, v245
	v_cmp_ngt_f32_e32 vcc, s90, v244
	s_nop 1
	v_cndmask_b32_e32 v246, v246, v247, vcc
	v_mul_f32_e32 v246, 0xc138aa3b, v246
	ds_write_b32 v240, v246 offset:40704
	s_mov_b64 exec, -1
	s_mov_b32 s38, s37
	s_waitcnt lgkmcnt(0)
	s_barrier
.Lscan1_staged:
	s_mov_b32 s66, 0xbfb8aa3b
	s_mov_b32 s67, 0xbd2ec3ff
	v_mov_b32_e32 v248, 0xbe1d955b
	v_mov_b32_e32 v249, 0xbee35847
	v_mov_b32_e32 v250, 0xbf75fdf0
	v_mov_b32_e32 v251, 0xbfb17218
	s_waitcnt vmcnt(0)
	s_cmp_eq_u32 s56, 0
	s_cbranch_scc1 .Lscan1_hzero
	v_lshlrev_b32_e32 v58, 16, v59
	v_and_b32_e32 v59, 0xffff0000, v59
	v_lshlrev_b32_e32 v60, 16, v61
	v_and_b32_e32 v61, 0xffff0000, v61
	v_lshlrev_b32_e32 v62, 16, v63
	v_and_b32_e32 v63, 0xffff0000, v63
	s_branch .Lscan1_hdone

.Lscan2_unit:
	s_and_b32 s37, s23, 15
	s_lshr_b32 s0, s23, 4
	s_lshl_b32 s0, s0, 3
	s_add_i32 s0, s0, s21
	s_mul_i32 s55, s0, 0x5f5
	s_lshr_b32 s55, s55, 16
	s_mul_i32 s56, s55, 43
	s_sub_i32 s56, s0, s56
	s_mul_i32 s57, s55, 0x810
	s_mul_i32 s39, s56, 48
	s_add_i32 s57, s57, s39
	s_mul_i32 s44, s57, 0x1800
	s_mul_hi_u32 s45, s57, 0x1800
	s_mul_i32 s39, s37, 0xc0
	s_add_i32 s39, s39, 0xc00
	s_add_u32 s44, s44, s39
	s_addc_u32 s45, s45, 0
	s_add_u32 s44, s44, s28
	s_addc_u32 s45, s45, s29
	s_add_u32 s62, s44, 0xffffb800
	s_addc_u32 s63, s45, -1
	global_load_dword v59, v233, s[62:63]
	s_add_u32 s62, s62, 0x1800
	s_addc_u32 s63, s63, 0
	global_load_dword v61, v233, s[62:63]
	s_add_u32 s62, s62, 0x1800
	s_addc_u32 s63, s63, 0
	global_load_dword v63, v233, s[62:63]
	s_mov_b64 s[62:63], s[44:45]
	global_load_dword v66, v233, s[62:63]
	s_add_u32 s62, s62, 0x1800
	s_addc_u32 s63, s63, 0
	global_load_dword v67, v233, s[62:63]
	s_add_u32 s62, s62, 0x1800
	s_addc_u32 s63, s63, 0
	global_load_dword v68, v233, s[62:63]
	s_add_u32 s62, s62, 0x1800
	s_addc_u32 s63, s63, 0
	global_load_dword v69, v233, s[62:63]
	s_add_u32 s62, s62, 0x1800
	s_addc_u32 s63, s63, 0
	global_load_dword v70, v233, s[62:63]
	s_add_u32 s62, s62, 0x1800
	s_addc_u32 s63, s63, 0
	global_load_dword v71, v233, s[62:63]
	s_add_u32 s62, s62, 0x1800
	s_addc_u32 s63, s63, 0
	global_load_dword v72, v233, s[62:63]
	s_add_u32 s62, s62, 0x1800
	s_addc_u32 s63, s63, 0
	global_load_dword v73, v233, s[62:63]
	s_add_u32 s62, s62, 0x1800
	s_addc_u32 s63, s63, 0
	global_load_dword v74, v233, s[62:63]
	s_add_u32 s62, s62, 0x1800
	s_addc_u32 s63, s63, 0
	global_load_dword v75, v233, s[62:63]
	s_add_u32 s62, s62, 0x1800
	s_addc_u32 s63, s63, 0
	global_load_dword v76, v233, s[62:63]
	s_add_u32 s62, s62, 0x1800
	s_addc_u32 s63, s63, 0
	global_load_dword v77, v233, s[62:63]
	s_add_u32 s62, s62, 0x1800
	s_addc_u32 s63, s63, 0
	global_load_dword v78, v233, s[62:63]
	s_add_u32 s62, s62, 0x1800
	s_addc_u32 s63, s63, 0
	global_load_dword v79, v233, s[62:63]
	s_add_u32 s62, s62, 0x1800
	s_addc_u32 s63, s63, 0
	global_load_dword v80, v233, s[62:63]
	s_add_u32 s62, s62, 0x1800
	s_addc_u32 s63, s63, 0
	global_load_dword v81, v233, s[62:63]
	s_add_u32 s62, s62, 0x1800
	s_addc_u32 s63, s63, 0
	s_mov_b64 s[44:45], s[62:63]
	s_mul_i32 s39, s37, 0x180
	s_add_u32 s62, s8, s39
	s_addc_u32 s63, s9, 0
	global_load_dwordx2 v[48:49], v234, s[62:63]
	s_add_u32 s62, s62, 0x1800
	s_addc_u32 s63, s63, 0
	global_load_dwordx2 v[50:51], v234, s[62:63]
	s_add_u32 s62, s62, 0x1800
	s_addc_u32 s63, s63, 0
	global_load_dwordx2 v[52:53], v234, s[62:63]
	s_add_u32 s62, s62, 0x1800
	s_addc_u32 s63, s63, 0
	global_load_dwordx2 v[54:55], v234, s[62:63]
	s_add_u32 s62, s10, s39
	s_addc_u32 s63, s11, 0
	global_load_dwordx2 v[56:57], v234, s[62:63]
	s_mul_i32 s39, s55, 43
	s_add_i32 s39, s39, s56
	s_mul_i32 s39, s39, 0x1800
	s_mul_i32 s0, s37, 0x180
	s_add_i32 s39, s39, s0
	s_add_u32 s62, s30, s39
	s_addc_u32 s63, s31, 0
	global_load_dwordx4 v[0:3], v237, s[62:63] offset:0
	global_load_dwordx4 v[4:7], v237, s[62:63] offset:64
	global_load_dwordx4 v[8:11], v237, s[62:63] offset:128
	global_load_dwordx4 v[12:15], v237, s[62:63] offset:192
	global_load_dwordx4 v[16:19], v237, s[62:63] offset:256
	global_load_dwordx4 v[20:23], v237, s[62:63] offset:320
	s_mul_i32 s6, s57, 0x1800
	s_mul_hi_u32 s7, s57, 0x1800
	s_mul_i32 s39, s37, 0xc0
	s_add_u32 s6, s6, s39
	s_addc_u32 s7, s7, 0
	s_add_u32 s6, s6, s28
	s_addc_u32 s7, s7, s29
	s_mul_i32 s100, s57, 0xc00
	s_mul_hi_u32 s101, s57, 0xc00
	s_add_u32 s100, s100, s39
	s_addc_u32 s101, s101, 0
	s_add_u32 s100, s100, s34
	s_addc_u32 s101, s101, s35
	s_cmp_eq_u32 s37, s38
	s_cbranch_scc1 .Lscan2_staged
	s_lshl_b32 s0, s20, 4
	s_add_i32 s0, s0, s37
	s_mul_i32 s0, s0, 0x4800
	s_add_u32 s62, s16, 0x3688000
	s_addc_u32 s63, s17, 0
	s_add_u32 s62, s62, s0
	s_addc_u32 s63, s63, 0
	v_add_u32_e32 v239, 0, v192
	v_mul_u32_u24_e32 v240, 0xaaab, v239
	v_lshrrev_b32_e32 v240, 19, v240
	v_mul_u32_u24_e32 v241, 12, v240
	v_sub_u32_e32 v241, v239, v241
	v_lshlrev_b32_e32 v241, 4, v241
	v_mul_u32_u24_e32 v118, 0xd0, v240
	v_add_u32_e32 v118, v118, v241
	v_mul_u32_u24_e32 v243, 0xc0, v240
	v_add_u32_e32 v243, v243, v241
	v_cmp_lt_u32_e32 vcc, 95, v240
	s_nop 1
	v_mov_b32_e32 v244, 0x8b800
	v_cndmask_b32_e32 v244, 0, v244, vcc
	v_add_u32_e32 v243, v243, v244
	global_load_dwordx4 v[98:101], v243, s[62:63]
	v_add_u32_e32 v239, 512, v192
	v_mul_u32_u24_e32 v240, 0xaaab, v239
	v_lshrrev_b32_e32 v240, 19, v240
	v_mul_u32_u24_e32 v241, 12, v240
	v_sub_u32_e32 v241, v239, v241
	v_lshlrev_b32_e32 v241, 4, v241
	v_mul_u32_u24_e32 v119, 0xd0, v240
	v_add_u32_e32 v119, v119, v241
	v_mul_u32_u24_e32 v243, 0xc0, v240
	v_add_u32_e32 v243, v243, v241
	v_cmp_lt_u32_e32 vcc, 95, v240
	s_nop 1
	v_mov_b32_e32 v244, 0x8b800
	v_cndmask_b32_e32 v244, 0, v244, vcc
	v_add_u32_e32 v243, v243, v244
	global_load_dwordx4 v[102:105], v243, s[62:63]
	v_add_u32_e32 v239, 1024, v192
	v_mul_u32_u24_e32 v240, 0xaaab, v239
	v_lshrrev_b32_e32 v240, 19, v240
	v_mul_u32_u24_e32 v241, 12, v240
	v_sub_u32_e32 v241, v239, v241
	v_lshlrev_b32_e32 v241, 4, v241
	v_mul_u32_u24_e32 v120, 0xd0, v240
	v_add_u32_e32 v120, v120, v241
	v_mul_u32_u24_e32 v243, 0xc0, v240
	v_add_u32_e32 v243, v243, v241
	v_cmp_lt_u32_e32 vcc, 95, v240
	s_nop 1
	v_mov_b32_e32 v244, 0x8b800
	v_cndmask_b32_e32 v244, 0, v244, vcc
	v_add_u32_e32 v243, v243, v244
	global_load_dwordx4 v[106:109], v243, s[62:63]
	v_add_u32_e32 v239, 1536, v192
	v_mul_u32_u24_e32 v240, 0xaaab, v239
	v_lshrrev_b32_e32 v240, 19, v240
	v_mul_u32_u24_e32 v241, 12, v240
	v_sub_u32_e32 v241, v239, v241
	v_lshlrev_b32_e32 v241, 4, v241
	v_mul_u32_u24_e32 v121, 0xd0, v240
	v_add_u32_e32 v121, v121, v241
	v_mul_u32_u24_e32 v243, 0xc0, v240
	v_add_u32_e32 v243, v243, v241
	v_cmp_lt_u32_e32 vcc, 95, v240
	s_nop 1
	v_mov_b32_e32 v244, 0x8b800
	v_cndmask_b32_e32 v244, 0, v244, vcc
	v_add_u32_e32 v243, v243, v244
	global_load_dwordx4 v[110:113], v243, s[62:63]
	v_add_u32_e32 v239, 2048, v192
	v_mul_u32_u24_e32 v240, 0xaaab, v239
	v_lshrrev_b32_e32 v240, 19, v240
	v_mul_u32_u24_e32 v241, 12, v240
	v_sub_u32_e32 v241, v239, v241
	v_lshlrev_b32_e32 v241, 4, v241
	v_mul_u32_u24_e32 v122, 0xd0, v240
	v_add_u32_e32 v122, v122, v241
	v_mul_u32_u24_e32 v243, 0xc0, v240
	v_add_u32_e32 v243, v243, v241
	v_cmp_lt_u32_e32 vcc, 95, v240
	s_nop 1
	v_mov_b32_e32 v244, 0x8b800
	v_cndmask_b32_e32 v244, 0, v244, vcc
	v_add_u32_e32 v243, v243, v244
	v_cmp_gt_u32_e32 vcc, 0x900, v239
	s_and_b64 exec, exec, vcc
	global_load_dwordx4 v[114:117], v243, s[62:63]
	s_mov_b64 exec, -1
	v_cmp_gt_u32_e32 vcc, 0x60, v192
	s_and_b64 exec, exec, vcc
	s_mul_i32 s0, s37, 0x180
	v_lshl_add_u32 v239, v192, 2, s0
	global_load_dword v123, v239, s[12:13]
	global_load_dword v124, v239, s[24:25]
	global_load_dword v125, v239, s[26:27]
	s_mov_b64 exec, -1
	s_waitcnt lgkmcnt(0)
	s_barrier
	s_waitcnt vmcnt(0)
	ds_write_b128 v118, v[98:101]
	ds_write_b128 v119, v[102:105]
	ds_write_b128 v120, v[106:109]
	ds_write_b128 v121, v[110:113]
	v_cmp_gt_u32_e32 vcc, 0x100, v192
	s_and_b64 exec, exec, vcc
	ds_write_b128 v122, v[114:117]
	s_mov_b64 exec, -1
	v_cmp_gt_u32_e32 vcc, 0x60, v192
	s_and_b64 exec, exec, vcc
	v_lshlrev_b32_e32 v240, 2, v192
	v_mul_f32_e32 v123, 0xbfb8aa3b, v123
	v_mul_f32_e32 v124, 0xbfb8aa3b, v124
	ds_write_b32 v240, v123 offset:39936
	ds_write_b32 v240, v124 offset:40320
	v_mul_f32_e32 v244, 0xbfb8aa3b, v125
	v_exp_f32_e32 v244, v244
	s_nop 0
	v_add_f32_e32 v245, 1.0, v244
	v_log_f32_e32 v245, v245
	v_fmamk_f32 v246, v244, 0xbe800000, v194
	v_fma_f32 v246, -v244, v246, 0.5
	v_fma_f32 v246, -v244, v246, 1.0
	v_mul_f32_e32 v246, v244, v246
	v_mul_f32_e32 v247, 0x3f317217, v245
	v_fma_f32 v247, v245, s76, -v247
	v_fmac_f32_e32 v247, 0x3377d1cf, v245
	v_fmac_f32_e32 v247, 0x3f317217, v245
	v_cmp_ngt_f32_e32 vcc, s90, v244
	s_nop 1
	v_cndmask_b32_e32 v246, v246, v247, vcc
	v_mul_f32_e32 v246, 0xc138aa3b, v246
	ds_write_b32 v240, v246 offset:40704
	s_mov_b64 exec, -1
	s_mov_b32 s38, s37
	s_waitcnt lgkmcnt(0)
	s_barrier
.Lscan2_staged:
	s_mov_b32 s4, 0xbfb8aa3b
	s_mov_b32 s5, 0xbd2ec3ff
	v_mov_b32_e32 v248, 0xbe1d955b
	v_mov_b32_e32 v249, 0xbee35847
	v_mov_b32_e32 v250, 0xbf75fdf0
	v_mov_b32_e32 v251, 0xbfb17218
	v_mov_b32_e32 v36, 0xbdd2d3e8
	v_mov_b32_e32 v37, 0xc0135761
	s_waitcnt vmcnt(0)
	s_cmp_eq_u32 s56, 0
	s_cbranch_scc1 .Lscan2_hzero
	v_lshlrev_b32_e32 v58, 16, v59
	v_and_b32_e32 v59, 0xffff0000, v59
	v_lshlrev_b32_e32 v60, 16, v61
	v_and_b32_e32 v61, 0xffff0000, v61
	v_lshlrev_b32_e32 v62, 16, v63
	v_and_b32_e32 v63, 0xffff0000, v63
	s_branch .Lscan2_hdone
